# strategy 7: folded the 0+x add at the head of the four softmax sum chains (exact)
# speedup vs baseline: 1.0042x; 1.0042x over previous
; DI float ex2(float x) { return __builtin_amdgcn_exp2f(x); }
; template <bool MASKED, class MF>
; DI void flash_update(f32x4 (&s)[4], float scl, float& mx, float& ls, f32x4 (&o)[8], MF maskfn, bool lane_on) {
;     ...
;   const float off = lane_on ? -mx * scl : -1e30f;
;   float rs = 0.f;
; #pragma unroll
;   for (int kt = 0; kt < 4; ++kt)
; #pragma unroll
;     for (int i = 0; i < 4; ++i) {
;       float pv = ex2(fmaf(s[kt][i], scl, off));
;       if (MASKED) pv = (s[kt][i] > -1e29f) ? pv : 0.f;
;       s[kt][i] = pv; rs += pv;
;     }
;   ls += rs;
.LBB0_578:
	v_mul_f32_e32 v15, 0xbfb8aa3b, v220
	v_fmamk_f32 v0, v172, 0x3fb8aa3b, v15
	v_exp_f32_e32 v0, v0
	v_fmamk_f32 v1, v173, 0x3fb8aa3b, v15
	v_exp_f32_e32 v1, v1
	v_fmamk_f32 v2, v174, 0x3fb8aa3b, v15
	v_exp_f32_e32 v2, v2
	v_fmamk_f32 v3, v175, 0x3fb8aa3b, v15
	v_exp_f32_e32 v3, v3
	v_add_f32_e32 v4, v1, v0
	v_add_f32_e32 v4, v2, v4
	v_add_f32_e32 v8, v3, v4
	v_fmamk_f32 v4, v164, 0x3fb8aa3b, v15
	v_exp_f32_e32 v4, v4
	v_fmamk_f32 v5, v165, 0x3fb8aa3b, v15
	v_exp_f32_e32 v5, v5
	v_fmamk_f32 v6, v166, 0x3fb8aa3b, v15
	v_exp_f32_e32 v6, v6
	v_fmamk_f32 v7, v167, 0x3fb8aa3b, v15
	v_exp_f32_e32 v7, v7
	v_add_f32_e32 v8, v4, v8
	v_add_f32_e32 v8, v5, v8
	v_add_f32_e32 v8, v6, v8
	v_add_f32_e32 v12, v7, v8
	v_fmamk_f32 v8, v168, 0x3fb8aa3b, v15
	v_exp_f32_e32 v8, v8
	v_fmamk_f32 v9, v169, 0x3fb8aa3b, v15
	v_exp_f32_e32 v9, v9
	v_fmamk_f32 v10, v170, 0x3fb8aa3b, v15
	v_exp_f32_e32 v10, v10
	v_fmamk_f32 v11, v171, 0x3fb8aa3b, v15
	v_exp_f32_e32 v11, v11
	v_add_f32_e32 v12, v8, v12
	v_add_f32_e32 v12, v9, v12
	v_add_f32_e32 v12, v10, v12
	v_add_f32_e32 v16, v11, v12
	v_fmamk_f32 v12, v160, 0x3fb8aa3b, v15
	v_exp_f32_e32 v12, v12
	v_fmamk_f32 v13, v161, 0x3fb8aa3b, v15
	v_exp_f32_e32 v13, v13
	v_fmamk_f32 v14, v162, 0x3fb8aa3b, v15
	v_exp_f32_e32 v14, v14
	v_fmac_f32_e32 v15, 0x3fb8aa3b, v163
	v_exp_f32_e32 v15, v15
	v_add_f32_e32 v16, v12, v16
	v_add_f32_e32 v16, v13, v16
	v_add_f32_e32 v16, v14, v16
	v_add_f32_e32 v16, v15, v16
	v_mul_f32_e32 v31, 0xbfb8aa3b, v221
	v_add_f32_e32 v213, v213, v16
	v_fmamk_f32 v16, v156, 0x3fb8aa3b, v31
	v_exp_f32_e32 v16, v16
	v_fmamk_f32 v17, v157, 0x3fb8aa3b, v31
	v_exp_f32_e32 v17, v17
	v_fmamk_f32 v18, v158, 0x3fb8aa3b, v31
	v_exp_f32_e32 v18, v18
	v_fmamk_f32 v19, v159, 0x3fb8aa3b, v31
	v_exp_f32_e32 v19, v19
	v_add_f32_e32 v20, v17, v16
	v_add_f32_e32 v20, v18, v20
	v_add_f32_e32 v24, v19, v20
	v_fmamk_f32 v20, v148, 0x3fb8aa3b, v31
	v_exp_f32_e32 v20, v20
	v_fmamk_f32 v21, v149, 0x3fb8aa3b, v31
	v_exp_f32_e32 v21, v21
	v_fmamk_f32 v22, v150, 0x3fb8aa3b, v31
	v_exp_f32_e32 v22, v22
	v_fmamk_f32 v23, v151, 0x3fb8aa3b, v31
	v_exp_f32_e32 v23, v23
	v_add_f32_e32 v24, v20, v24
	v_add_f32_e32 v24, v21, v24
	v_add_f32_e32 v24, v22, v24
	v_add_f32_e32 v28, v23, v24
	v_fmamk_f32 v24, v152, 0x3fb8aa3b, v31
	v_exp_f32_e32 v24, v24
	v_fmamk_f32 v25, v153, 0x3fb8aa3b, v31
	v_exp_f32_e32 v25, v25
	v_fmamk_f32 v26, v154, 0x3fb8aa3b, v31
	v_exp_f32_e32 v26, v26
	v_fmamk_f32 v27, v155, 0x3fb8aa3b, v31
	v_exp_f32_e32 v27, v27
	v_add_f32_e32 v28, v24, v28
	v_add_f32_e32 v28, v25, v28
	v_add_f32_e32 v28, v26, v28
	v_add_f32_e32 v148, v27, v28
	v_fmamk_f32 v28, v144, 0x3fb8aa3b, v31
	v_exp_f32_e32 v28, v28
	v_fmamk_f32 v29, v145, 0x3fb8aa3b, v31
	v_exp_f32_e32 v29, v29
	v_fmamk_f32 v30, v146, 0x3fb8aa3b, v31
	v_exp_f32_e32 v30, v30
	v_fmac_f32_e32 v31, 0x3fb8aa3b, v147
	v_exp_f32_e32 v31, v31
	v_add_f32_e32 v144, v28, v148
	v_add_f32_e32 v144, v29, v144
	v_add_f32_e32 v144, v30, v144
	v_add_f32_e32 v231, v31, v144

; DI float ex2(float x) { return __builtin_amdgcn_exp2f(x); }
; template <bool MASKED, class MF>
; DI void flash_update(f32x4 (&s)[4], float scl, float& mx, float& ls, f32x4 (&o)[8], MF maskfn, bool lane_on) {
;     ...
;   const float off = lane_on ? -mx * scl : -1e30f;
;   float rs = 0.f;
; #pragma unroll
;   for (int kt = 0; kt < 4; ++kt)
; #pragma unroll
;     for (int i = 0; i < 4; ++i) {
;       float pv = ex2(fmaf(s[kt][i], scl, off));
;       if (MASKED) pv = (s[kt][i] > -1e29f) ? pv : 0.f;
;       s[kt][i] = pv; rs += pv;
;     }
;   ls += rs;
.LBB0_822:
	v_mul_f32_e32 v0, 0xbe0293ee, v175
	v_cndmask_b32_e64 v15, v231, v0, s[38:39]
	v_fmamk_f32 v0, v114, 0x3e0293ee, v15
	v_exp_f32_e32 v0, v0
	v_fmamk_f32 v1, v115, 0x3e0293ee, v15
	v_exp_f32_e32 v1, v1
	v_fmamk_f32 v2, v116, 0x3e0293ee, v15
	v_exp_f32_e32 v2, v2
	v_fmamk_f32 v3, v117, 0x3e0293ee, v15
	v_exp_f32_e32 v3, v3
	v_add_f32_e32 v4, v1, v0
	v_add_f32_e32 v4, v2, v4
	v_add_f32_e32 v8, v3, v4
	v_fmamk_f32 v4, v118, 0x3e0293ee, v15
	v_exp_f32_e32 v4, v4
	v_fmamk_f32 v5, v119, 0x3e0293ee, v15
	v_exp_f32_e32 v5, v5
	v_fmamk_f32 v6, v120, 0x3e0293ee, v15
	v_exp_f32_e32 v6, v6
	v_fmamk_f32 v7, v121, 0x3e0293ee, v15
	v_exp_f32_e32 v7, v7
	v_add_f32_e32 v8, v4, v8
	v_add_f32_e32 v8, v5, v8
	v_add_f32_e32 v8, v6, v8
	v_add_f32_e32 v12, v7, v8
	v_fmamk_f32 v8, v122, 0x3e0293ee, v15
	v_exp_f32_e32 v8, v8
	v_fmamk_f32 v9, v123, 0x3e0293ee, v15
	v_exp_f32_e32 v9, v9
	v_fmamk_f32 v10, v124, 0x3e0293ee, v15
	v_exp_f32_e32 v10, v10
	v_fmamk_f32 v11, v125, 0x3e0293ee, v15
	v_exp_f32_e32 v11, v11
	v_add_f32_e32 v12, v8, v12
	v_add_f32_e32 v12, v9, v12
	v_add_f32_e32 v12, v10, v12
	v_add_f32_e32 v178, v11, v12
	v_fmamk_f32 v12, v126, 0x3e0293ee, v15
	v_exp_f32_e32 v12, v12
	v_fmamk_f32 v13, v127, 0x3e0293ee, v15
	v_exp_f32_e32 v13, v13
	v_fmamk_f32 v14, v128, 0x3e0293ee, v15
	v_exp_f32_e32 v14, v14
	v_fmac_f32_e32 v15, 0x3e0293ee, v129
	v_exp_f32_e32 v15, v15
	v_add_f32_e32 v178, v12, v178
	v_add_f32_e32 v178, v13, v178
	v_add_f32_e32 v178, v14, v178
	v_add_f32_e32 v178, v15, v178
	s_mov_b64 s[48:49], 0

; DI float ex2(float x) { return __builtin_amdgcn_exp2f(x); }
; template <bool MASKED, class MF>
; DI void flash_update(f32x4 (&s)[4], float scl, float& mx, float& ls, f32x4 (&o)[8], MF maskfn, bool lane_on) {
;     ...
;   const float off = lane_on ? -mx * scl : -1e30f;
;   float rs = 0.f;
; #pragma unroll
;   for (int kt = 0; kt < 4; ++kt)
; #pragma unroll
;     for (int i = 0; i < 4; ++i) {
;       float pv = ex2(fmaf(s[kt][i], scl, off));
;       if (MASKED) pv = (s[kt][i] > -1e29f) ? pv : 0.f;
;       s[kt][i] = pv; rs += pv;
;     }
;   ls += rs;
.LBB0_852:
	v_mul_f32_e32 v15, 0xbe0293ee, v246
	v_fmamk_f32 v0, v158, 0x3e0293ee, v15
	v_exp_f32_e32 v0, v0
	v_fmamk_f32 v1, v159, 0x3e0293ee, v15
	v_exp_f32_e32 v1, v1
	v_fmamk_f32 v2, v160, 0x3e0293ee, v15
	v_exp_f32_e32 v2, v2
	v_fmamk_f32 v3, v161, 0x3e0293ee, v15
	v_exp_f32_e32 v3, v3
	v_add_f32_e32 v4, v1, v0
	v_add_f32_e32 v4, v2, v4
	v_add_f32_e32 v8, v3, v4
	v_fmamk_f32 v4, v154, 0x3e0293ee, v15
	v_exp_f32_e32 v4, v4
	v_fmamk_f32 v5, v155, 0x3e0293ee, v15
	v_exp_f32_e32 v5, v5
	v_fmamk_f32 v6, v156, 0x3e0293ee, v15
	v_exp_f32_e32 v6, v6
	v_fmamk_f32 v7, v157, 0x3e0293ee, v15
	v_exp_f32_e32 v7, v7
	v_add_f32_e32 v8, v4, v8
	v_add_f32_e32 v8, v5, v8
	v_add_f32_e32 v8, v6, v8
	v_add_f32_e32 v12, v7, v8
	v_fmamk_f32 v8, v150, 0x3e0293ee, v15
	v_exp_f32_e32 v8, v8
	v_fmamk_f32 v9, v151, 0x3e0293ee, v15
	v_exp_f32_e32 v9, v9
	v_fmamk_f32 v10, v152, 0x3e0293ee, v15
	v_exp_f32_e32 v10, v10
	v_fmamk_f32 v11, v153, 0x3e0293ee, v15
	v_exp_f32_e32 v11, v11
	v_add_f32_e32 v12, v8, v12
	v_add_f32_e32 v12, v9, v12
	v_add_f32_e32 v12, v10, v12
	v_add_f32_e32 v150, v11, v12
	v_fmamk_f32 v12, v146, 0x3e0293ee, v15
	v_exp_f32_e32 v12, v12
	v_fmamk_f32 v13, v147, 0x3e0293ee, v15
	v_exp_f32_e32 v13, v13
	v_fmamk_f32 v14, v148, 0x3e0293ee, v15
	v_exp_f32_e32 v14, v14
	v_fmac_f32_e32 v15, 0x3e0293ee, v149
	v_exp_f32_e32 v15, v15
	v_add_f32_e32 v146, v12, v150
	v_add_f32_e32 v146, v13, v146
	v_add_f32_e32 v146, v14, v146
	v_mov_b64_e32 v[164:165], v[128:129]
	v_mov_b64_e32 v[168:169], v[124:125]
	v_mov_b64_e32 v[172:173], v[120:121]
	v_mov_b64_e32 v[176:177], v[116:117]
	v_mov_b64_e32 v[180:181], v[112:113]
	v_mov_b64_e32 v[184:185], v[108:109]
	v_mov_b64_e32 v[188:189], v[104:105]
	v_mov_b64_e32 v[192:193], v[100:101]
	v_add_f32_e32 v251, v15, v146
	v_mov_b32_e32 v248, v246
	v_mov_b32_e32 v250, v244
	v_mov_b64_e32 v[162:163], v[126:127]
	v_mov_b64_e32 v[166:167], v[122:123]
	v_mov_b64_e32 v[170:171], v[118:119]
	v_mov_b64_e32 v[174:175], v[114:115]
	v_mov_b64_e32 v[178:179], v[110:111]
	v_mov_b64_e32 v[182:183], v[106:107]
	v_mov_b64_e32 v[186:187], v[102:103]
	v_mov_b64_e32 v[190:191], v[98:99]
